# prep: the W output stores also tagged nt like the other prep outputs (cache-policy consistency), on top of the combined stack
# speedup vs baseline: 1.0061x; 1.0005x over previous
.Lpe_w:
	s_sub_u32 s0, s6, 4
	s_lshl_b32 s1, s0, 6
	v_mul_u32_u24_e32 v6, 0x440, v3
	v_lshl_add_u32 v6, v1, 1, v6
	v_add_u32_e32 v6, s1, v6
	s_lshl_b32 s1, s0, 10
	v_lshrrev_b32_e32 v9, 1, v3
	v_lshlrev_b32_e32 v9, 8, v9
	v_lshl_add_u32 v9, v1, 4, v9
	v_and_b32_e32 v26, 1, v3
	v_lshl_add_u32 v9, v26, 3, v9
	v_add_u32_e32 v9, s1, v9
	s_add_u32 s4, s10, s16
	s_addc_u32 s5, s11, s17
	s_add_u32 s4, s4, 0x11800000
	s_addc_u32 s5, s5, 0
	ds_read_b128 v[10:13], v7 offset:256
	ds_read_b128 v[14:17], v7 offset:0
	ds_read_u16 v18, v6 offset:0
	ds_read_u16 v19, v6 offset:272
	ds_read_u16 v20, v6 offset:544
	ds_read_u16 v21, v6 offset:816
	ds_read_u16 v22, v6 offset:32
	ds_read_u16 v23, v6 offset:304
	ds_read_u16 v24, v6 offset:576
	ds_read_u16 v25, v6 offset:848
	ds_read_b64 v[164:165], v4 offset:0
	ds_read_b128 v[136:139], v7 offset:320
	ds_read_b128 v[140:143], v7 offset:64
	ds_read_u16 v144, v6 offset:4352
	ds_read_u16 v145, v6 offset:4624
	ds_read_u16 v146, v6 offset:4896
	ds_read_u16 v147, v6 offset:5168
	ds_read_u16 v148, v6 offset:4384
	ds_read_u16 v149, v6 offset:4656
	ds_read_u16 v150, v6 offset:4928
	ds_read_u16 v151, v6 offset:5200
	ds_read_b64 v[180:181], v5 offset:2304
	ds_read_b64 v[204:205], v4 offset:512
	s_waitcnt lgkmcnt(12)
	v_mul_f32_e32 v14, 0x3fb8aa3b, v14
	v_mul_f32_e32 v15, 0x3fb8aa3b, v15
	v_mul_f32_e32 v16, 0x3fb8aa3b, v16
	v_mul_f32_e32 v17, 0x3fb8aa3b, v17
	v_exp_f32_e32 v14, v14
	v_exp_f32_e32 v15, v15
	v_exp_f32_e32 v16, v16
	v_exp_f32_e32 v17, v17
	v_lshlrev_b32_e32 v18, 16, v18
	v_lshlrev_b32_e32 v19, 16, v19
	v_lshlrev_b32_e32 v20, 16, v20
	v_lshlrev_b32_e32 v21, 16, v21
	v_lshlrev_b32_e32 v22, 16, v22
	v_lshlrev_b32_e32 v23, 16, v23
	v_lshlrev_b32_e32 v24, 16, v24
	v_lshlrev_b32_e32 v25, 16, v25
	v_mul_f32_e32 v18, v10, v18
	v_mul_f32_e32 v19, v11, v19
	v_mul_f32_e32 v20, v12, v20
	v_mul_f32_e32 v21, v13, v21
	v_mul_f32_e32 v22, v10, v22
	v_mul_f32_e32 v23, v11, v23
	v_mul_f32_e32 v24, v12, v24
	v_mul_f32_e32 v25, v13, v25
	v_mul_f32_e32 v18, v18, v14
	v_mul_f32_e32 v19, v19, v15
	v_mul_f32_e32 v20, v20, v16
	v_mul_f32_e32 v21, v21, v17
	v_mul_f32_e32 v22, v22, v14
	v_mul_f32_e32 v23, v23, v15
	v_mul_f32_e32 v24, v24, v16
	v_mul_f32_e32 v25, v25, v17
	v_cvt_pk_bf16_f32 v246, v18, v19
	v_cvt_pk_bf16_f32 v247, v20, v21
	v_cvt_pk_bf16_f32 v160, v22, v23
	v_cvt_pk_bf16_f32 v161, v24, v25
	v_mfma_f32_16x16x16_bf16 v[18:21], v[164:165], v[246:247], 0
	s_nop 0
	v_mfma_f32_16x16x16_bf16 v[22:25], v[164:165], v[160:161], 0
	v_mfma_f32_16x16x16_bf16 v[168:171], v[246:247], v[164:165], 0
	v_mfma_f32_16x16x16_bf16 v[172:175], v[160:161], v[164:165], 0
	ds_read_b128 v[176:179], v7 offset:384
	ds_read_b128 v[184:187], v7 offset:128
	ds_read_u16 v188, v6 offset:8704
	ds_read_u16 v189, v6 offset:8976
	ds_read_u16 v190, v6 offset:9248
	ds_read_u16 v191, v6 offset:9520
	ds_read_u16 v192, v6 offset:8736
	ds_read_u16 v193, v6 offset:9008
	ds_read_u16 v194, v6 offset:9280
	ds_read_u16 v195, v6 offset:9552
	ds_read_b64 v[162:163], v5 offset:4608
	ds_read_b64 v[196:197], v5 offset:4640
	ds_read_b64 v[198:199], v4 offset:1024
	v_cvt_pk_bf16_f32 v200, v18, v19
	v_cvt_pk_bf16_f32 v201, v20, v21
	v_cvt_pk_bf16_f32 v202, v22, v23
	v_cvt_pk_bf16_f32 v203, v24, v25
	v_cvt_pk_bf16_f32 v168, v168, v169
	v_cvt_pk_bf16_f32 v169, v170, v171
	global_store_dwordx2 v9, v[168:169], s[4:5] offset:0 nt
	v_cvt_pk_bf16_f32 v172, v172, v173
	v_cvt_pk_bf16_f32 v173, v174, v175
	global_store_dwordx2 v9, v[172:173], s[4:5] offset:512 nt
	s_add_u32 s4, s4, 0x1000
	s_addc_u32 s5, s5, 0
	s_waitcnt lgkmcnt(14)
	v_mfma_f32_16x16x16_bf16 v[234:237], v[180:181], v[200:201], 0
	v_mfma_f32_16x16x16_bf16 v[238:241], v[180:181], v[202:203], 0
	s_waitcnt lgkmcnt(13)
	v_mul_f32_e32 v140, 0x3fb8aa3b, v140
	v_mul_f32_e32 v141, 0x3fb8aa3b, v141
	v_mul_f32_e32 v142, 0x3fb8aa3b, v142
	v_mul_f32_e32 v143, 0x3fb8aa3b, v143
	v_exp_f32_e32 v140, v140
	v_exp_f32_e32 v141, v141
	v_exp_f32_e32 v142, v142
	v_exp_f32_e32 v143, v143
	v_lshlrev_b32_e32 v144, 16, v144
	v_lshlrev_b32_e32 v145, 16, v145
	v_lshlrev_b32_e32 v146, 16, v146
	v_lshlrev_b32_e32 v147, 16, v147
	v_lshlrev_b32_e32 v148, 16, v148
	v_lshlrev_b32_e32 v149, 16, v149
	v_lshlrev_b32_e32 v150, 16, v150
	v_lshlrev_b32_e32 v151, 16, v151
	v_mul_f32_e32 v144, v136, v144
	v_mul_f32_e32 v145, v137, v145
	v_mul_f32_e32 v146, v138, v146
	v_mul_f32_e32 v147, v139, v147
	v_mul_f32_e32 v148, v136, v148
	v_mul_f32_e32 v149, v137, v149
	v_mul_f32_e32 v150, v138, v150
	v_mul_f32_e32 v151, v139, v151
	v_mul_f32_e32 v144, v144, v140
	v_mul_f32_e32 v145, v145, v141
	v_mul_f32_e32 v146, v146, v142
	v_mul_f32_e32 v147, v147, v143
	v_mul_f32_e32 v148, v148, v140
	v_mul_f32_e32 v149, v149, v141
	v_mul_f32_e32 v150, v150, v142
	v_mul_f32_e32 v151, v151, v143
	v_sub_f32_e32 v234, v144, v234
	v_sub_f32_e32 v235, v145, v235
	v_sub_f32_e32 v236, v146, v236
	v_sub_f32_e32 v237, v147, v237
	v_cvt_pk_bf16_f32 v246, v234, v235
	v_cvt_pk_bf16_f32 v247, v236, v237
	v_sub_f32_e32 v238, v148, v238
	v_sub_f32_e32 v239, v149, v239
	v_sub_f32_e32 v240, v150, v240
	v_sub_f32_e32 v241, v151, v241
	v_cvt_pk_bf16_f32 v160, v238, v239
	v_cvt_pk_bf16_f32 v161, v240, v241
	v_mfma_f32_16x16x16_bf16 v[234:237], v[204:205], v[246:247], 0
	s_nop 0
	v_mfma_f32_16x16x16_bf16 v[238:241], v[204:205], v[160:161], 0
	v_mfma_f32_16x16x16_bf16 v[242:245], v[246:247], v[204:205], 0
	v_mfma_f32_16x16x16_bf16 v[10:13], v[160:161], v[204:205], 0
	ds_read_b128 v[14:17], v7 offset:448
	ds_read_b128 v[18:21], v7 offset:192
	ds_read_u16 v22, v6 offset:13056
	ds_read_u16 v23, v6 offset:13328
	ds_read_u16 v24, v6 offset:13600
	ds_read_u16 v25, v6 offset:13872
	ds_read_u16 v168, v6 offset:13088
	ds_read_u16 v169, v6 offset:13360
	ds_read_u16 v170, v6 offset:13632
	ds_read_u16 v171, v6 offset:13904
	ds_read_b64 v[164:165], v5 offset:6912
	ds_read_b64 v[180:181], v5 offset:6944
	ds_read_b64 v[172:173], v5 offset:6976
	ds_read_b64 v[174:175], v4 offset:1536
	v_cvt_pk_bf16_f32 v136, v234, v235
	v_cvt_pk_bf16_f32 v137, v236, v237
	v_cvt_pk_bf16_f32 v138, v238, v239
	v_cvt_pk_bf16_f32 v139, v240, v241
	v_cvt_pk_bf16_f32 v242, v242, v243
	v_cvt_pk_bf16_f32 v243, v244, v245
	global_store_dwordx2 v9, v[242:243], s[4:5] offset:0 nt
	v_cvt_pk_bf16_f32 v10, v10, v11
	v_cvt_pk_bf16_f32 v11, v12, v13
	global_store_dwordx2 v9, v[10:11], s[4:5] offset:512 nt
	s_add_u32 s4, s4, 0x1000
	s_addc_u32 s5, s5, 0
	s_waitcnt lgkmcnt(14)
	v_mfma_f32_16x16x16_bf16 v[140:143], v[162:163], v[200:201], 0
	v_mfma_f32_16x16x16_bf16 v[144:147], v[162:163], v[202:203], 0
	v_mfma_f32_16x16x16_bf16 v[140:143], v[196:197], v[136:137], v[140:143]
	v_mfma_f32_16x16x16_bf16 v[144:147], v[196:197], v[138:139], v[144:147]
	s_waitcnt lgkmcnt(14)
	v_mul_f32_e32 v184, 0x3fb8aa3b, v184
	v_mul_f32_e32 v185, 0x3fb8aa3b, v185
	v_mul_f32_e32 v186, 0x3fb8aa3b, v186
	v_mul_f32_e32 v187, 0x3fb8aa3b, v187
	v_exp_f32_e32 v184, v184
	v_exp_f32_e32 v185, v185
	v_exp_f32_e32 v186, v186
	v_exp_f32_e32 v187, v187
	v_lshlrev_b32_e32 v188, 16, v188
	v_lshlrev_b32_e32 v189, 16, v189
	v_lshlrev_b32_e32 v190, 16, v190
	v_lshlrev_b32_e32 v191, 16, v191
	v_lshlrev_b32_e32 v192, 16, v192
	v_lshlrev_b32_e32 v193, 16, v193
	v_lshlrev_b32_e32 v194, 16, v194
	v_lshlrev_b32_e32 v195, 16, v195
	v_mul_f32_e32 v188, v176, v188
	v_mul_f32_e32 v189, v177, v189
	v_mul_f32_e32 v190, v178, v190
	v_mul_f32_e32 v191, v179, v191
	v_mul_f32_e32 v192, v176, v192
	v_mul_f32_e32 v193, v177, v193
	v_mul_f32_e32 v194, v178, v194
	v_mul_f32_e32 v195, v179, v195
	v_mul_f32_e32 v188, v188, v184
	v_mul_f32_e32 v189, v189, v185
	v_mul_f32_e32 v190, v190, v186
	v_mul_f32_e32 v191, v191, v187
	v_mul_f32_e32 v192, v192, v184
	v_mul_f32_e32 v193, v193, v185
	v_mul_f32_e32 v194, v194, v186
	v_mul_f32_e32 v195, v195, v187
	v_sub_f32_e32 v140, v188, v140
	v_sub_f32_e32 v141, v189, v141
	v_sub_f32_e32 v142, v190, v142
	v_sub_f32_e32 v143, v191, v143
	v_cvt_pk_bf16_f32 v246, v140, v141
	v_cvt_pk_bf16_f32 v247, v142, v143
	v_sub_f32_e32 v144, v192, v144
	v_sub_f32_e32 v145, v193, v145
	v_sub_f32_e32 v146, v194, v146
	v_sub_f32_e32 v147, v195, v147
	v_cvt_pk_bf16_f32 v160, v144, v145
	v_cvt_pk_bf16_f32 v161, v146, v147
	v_mfma_f32_16x16x16_bf16 v[140:143], v[198:199], v[246:247], 0
	s_nop 0
	v_mfma_f32_16x16x16_bf16 v[144:147], v[198:199], v[160:161], 0
	v_mfma_f32_16x16x16_bf16 v[148:151], v[246:247], v[198:199], 0
	v_mfma_f32_16x16x16_bf16 v[234:237], v[160:161], v[198:199], 0
	s_nop 3
	v_cvt_pk_bf16_f32 v204, v140, v141
	v_cvt_pk_bf16_f32 v205, v142, v143
	v_cvt_pk_bf16_f32 v162, v144, v145
	v_cvt_pk_bf16_f32 v163, v146, v147
	v_cvt_pk_bf16_f32 v148, v148, v149
	v_cvt_pk_bf16_f32 v149, v150, v151
	global_store_dwordx2 v9, v[148:149], s[4:5] offset:0 nt
	v_cvt_pk_bf16_f32 v234, v234, v235
	v_cvt_pk_bf16_f32 v235, v236, v237
	global_store_dwordx2 v9, v[234:235], s[4:5] offset:512 nt
	s_add_u32 s4, s4, 0x1000
	s_addc_u32 s5, s5, 0
	s_waitcnt lgkmcnt(1)
	v_mfma_f32_16x16x16_bf16 v[238:241], v[164:165], v[200:201], 0
	v_mfma_f32_16x16x16_bf16 v[242:245], v[164:165], v[202:203], 0
	v_mfma_f32_16x16x16_bf16 v[238:241], v[180:181], v[136:137], v[238:241]
	v_mfma_f32_16x16x16_bf16 v[242:245], v[180:181], v[138:139], v[242:245]
	v_mfma_f32_16x16x16_bf16 v[238:241], v[172:173], v[204:205], v[238:241]
	v_mfma_f32_16x16x16_bf16 v[242:245], v[172:173], v[162:163], v[242:245]
	s_waitcnt lgkmcnt(0)
	v_mul_f32_e32 v18, 0x3fb8aa3b, v18
	v_mul_f32_e32 v19, 0x3fb8aa3b, v19
	v_mul_f32_e32 v20, 0x3fb8aa3b, v20
	v_mul_f32_e32 v21, 0x3fb8aa3b, v21
	v_exp_f32_e32 v18, v18
	v_exp_f32_e32 v19, v19
	v_exp_f32_e32 v20, v20
	v_exp_f32_e32 v21, v21
	v_lshlrev_b32_e32 v22, 16, v22
	v_lshlrev_b32_e32 v23, 16, v23
	v_lshlrev_b32_e32 v24, 16, v24
	v_lshlrev_b32_e32 v25, 16, v25
	v_lshlrev_b32_e32 v168, 16, v168
	v_lshlrev_b32_e32 v169, 16, v169
	v_lshlrev_b32_e32 v170, 16, v170
	v_lshlrev_b32_e32 v171, 16, v171
	v_mul_f32_e32 v22, v14, v22
	v_mul_f32_e32 v23, v15, v23
	v_mul_f32_e32 v24, v16, v24
	v_mul_f32_e32 v25, v17, v25
	v_mul_f32_e32 v168, v14, v168
	v_mul_f32_e32 v169, v15, v169
	v_mul_f32_e32 v170, v16, v170
	v_mul_f32_e32 v171, v17, v171
	v_mul_f32_e32 v22, v22, v18
	v_mul_f32_e32 v23, v23, v19
	v_mul_f32_e32 v24, v24, v20
	v_mul_f32_e32 v25, v25, v21
	v_mul_f32_e32 v168, v168, v18
	v_mul_f32_e32 v169, v169, v19
	v_mul_f32_e32 v170, v170, v20
	v_mul_f32_e32 v171, v171, v21
	v_sub_f32_e32 v238, v22, v238
	v_sub_f32_e32 v239, v23, v239
	v_sub_f32_e32 v240, v24, v240
	v_sub_f32_e32 v241, v25, v241
	v_cvt_pk_bf16_f32 v196, v238, v239
	v_cvt_pk_bf16_f32 v197, v240, v241
	v_sub_f32_e32 v242, v168, v242
	v_sub_f32_e32 v243, v169, v243
	v_sub_f32_e32 v244, v170, v244
	v_sub_f32_e32 v245, v171, v245
	v_cvt_pk_bf16_f32 v246, v242, v243
	v_cvt_pk_bf16_f32 v247, v244, v245
	v_mfma_f32_16x16x16_bf16 v[10:13], v[196:197], v[174:175], 0
	s_nop 0
	v_mfma_f32_16x16x16_bf16 v[176:179], v[246:247], v[174:175], 0
	s_nop 5
	v_cvt_pk_bf16_f32 v10, v10, v11
	v_cvt_pk_bf16_f32 v11, v12, v13
	global_store_dwordx2 v9, v[10:11], s[4:5] offset:0 nt
	v_cvt_pk_bf16_f32 v176, v176, v177
	v_cvt_pk_bf16_f32 v177, v178, v179
	global_store_dwordx2 v9, v[176:177], s[4:5] offset:512 nt
